# v70 = v66 (deferred row-sum + LRU fold) + past PV-stretch packed ops split into scalar pairs
# speedup vs baseline: 1.0070x; 1.0070x over previous
.LBB0_259:
	ds_read_b128 v[72:75], v116 offset:64
	ds_read_b128 v[100:103], v116 offset:2368
	v_mov_b32_e32 v163, v164
	v_add_u32_e32 v164, s0, v121
	s_waitcnt lgkmcnt(2)
	v_mfma_f32_16x16x32_bf16 v[198:201], v[234:237], v[40:43], 0
	v_mov_b32_e32 v165, v166
	v_add_u32_e32 v166, 0x2000, v164
	v_add_u32_e32 v167, 0x4000, v164
	v_mfma_f32_16x16x32_bf16 v[104:107], v[234:237], v[36:39], 0
	ds_read_b128 v[80:83], v116 offset:4608
	ds_read_b128 v[76:79], v116 offset:4672
	s_addk_i32 s0, 0x80
	s_cmpk_eq_i32 s0, 0x200
	v_mfma_f32_16x16x32_bf16 v[68:71], v[238:241], v[40:43], 0
	v_mfma_f32_16x16x32_bf16 v[64:67], v[238:241], v[36:39], 0
	s_waitcnt lgkmcnt(1)
	v_mfma_f32_16x16x32_bf16 v[92:95], v[80:83], v[40:43], 0
	v_mfma_f32_16x16x32_bf16 v[84:87], v[80:83], v[36:39], 0
	ds_read_b128 v[88:91], v116 offset:6912
	ds_read_b128 v[80:83], v116 offset:6976
	v_add_u32_e32 v116, 0x2400, v116
	s_waitcnt lgkmcnt(1)
	v_mfma_f32_16x16x32_bf16 v[96:99], v[88:91], v[40:43], 0
	v_mfma_f32_16x16x32_bf16 v[88:91], v[88:91], v[36:39], 0
	v_mfma_f32_16x16x32_bf16 v[68:71], v[72:75], v[44:47], v[68:71]
	v_mfma_f32_16x16x32_bf16 v[72:75], v[72:75], v[32:35], v[64:67]
	v_mfma_f32_16x16x32_bf16 v[64:67], v[100:103], v[44:47], v[198:201]
	v_mfma_f32_16x16x32_bf16 v[100:103], v[100:103], v[32:35], v[104:107]
	s_nop 2
	ds_read2_b64 v[104:107], v164 offset1:4
	ds_read2_b64 v[198:201], v164 offset0:8 offset1:12
	v_add_u32_e32 v164, 0x6000, v164
	v_mfma_f32_16x16x32_bf16 v[92:95], v[76:79], v[44:47], v[92:95]
	v_mfma_f32_16x16x32_bf16 v[76:79], v[76:79], v[32:35], v[84:87]
	s_nop 2
	ds_read2_b64 v[84:87], v166 offset0:32 offset1:36
	ds_read2_b64 v[202:205], v166 offset0:40 offset1:44
	ds_read2_b64 v[206:209], v167 offset0:64 offset1:68
	ds_read2_b64 v[210:213], v167 offset0:72 offset1:76
	ds_read2_b64 v[214:217], v164 offset0:96 offset1:100
	ds_read2_b64 v[218:221], v164 offset0:104 offset1:108
	s_waitcnt lgkmcnt(8)
	v_mfma_f32_16x16x32_bf16 v[96:99], v[80:83], v[44:47], v[96:99]
	v_mfma_f32_16x16x32_bf16 v[80:83], v[80:83], v[32:35], v[88:91]
	s_nop 2
	v_max3_f32 v88, v68, s4, v69
	v_max3_f32 v89, v72, s4, v73
	v_max3_f32 v88, v88, v70, v71
	v_max3_f32 v89, v89, v74, v75
	v_max3_f32 v88, v88, v64, v65
	v_max3_f32 v89, v89, v100, v101
	v_max3_f32 v88, v88, v66, v67
	v_max3_f32 v89, v89, v102, v103
	v_max3_f32 v88, v88, v92, v93
	v_max3_f32 v89, v89, v76, v77
	v_max3_f32 v88, v88, v94, v95
	v_max3_f32 v89, v89, v78, v79
	v_max3_f32 v88, v88, v96, v97
	v_max3_f32 v89, v89, v80, v81
	v_max3_f32 v88, v88, v98, v99
	v_max3_f32 v89, v89, v82, v83
	v_mov_b32_e32 v90, v88
	v_mov_b32_e32 v91, v89
	s_nop 0
	v_permlane16_swap_b32_e32 v90, v88
	v_permlane16_swap_b32_e32 v91, v89
	v_max_f32_e32 v88, v88, v90
	v_max_f32_e32 v89, v89, v91
	v_mov_b32_e32 v90, v88
	v_mov_b32_e32 v91, v89
	s_nop 0
	v_permlane32_swap_b32_e32 v90, v88
	v_permlane32_swap_b32_e32 v91, v89
	v_max3_f32 v164, v163, v89, v91
	v_max3_f32 v166, v165, v88, v90
	v_sub_f32_e32 v89, v163, v164
	v_sub_f32_e32 v88, v165, v166
	v_sub_f32_e32 v90, 0, v166
	v_sub_f32_e32 v178, 0, v164
	v_pk_add_f32 v[68:69], v[68:69], v[90:91] op_sel_hi:[1,0]
	v_pk_add_f32 v[70:71], v[70:71], v[90:91] op_sel_hi:[1,0]
	v_pk_add_f32 v[72:73], v[72:73], v[178:179] op_sel_hi:[1,0]
	v_pk_add_f32 v[74:75], v[74:75], v[178:179] op_sel_hi:[1,0]
	v_exp_f32_e32 v88, v88
	v_exp_f32_e32 v89, v89
	v_pk_add_f32 v[64:65], v[64:65], v[90:91] op_sel_hi:[1,0]
	v_pk_add_f32 v[66:67], v[66:67], v[90:91] op_sel_hi:[1,0]
	v_mov_b32_e32 v186, v89
	v_exp_f32_e32 v68, v68
	v_exp_f32_e32 v69, v69
	v_exp_f32_e32 v70, v70
	v_exp_f32_e32 v71, v71
	v_pk_add_f32 v[100:101], v[100:101], v[178:179] op_sel_hi:[1,0]
	v_pk_add_f32 v[102:103], v[102:103], v[178:179] op_sel_hi:[1,0]
	v_exp_f32_e32 v72, v72
	v_exp_f32_e32 v73, v73
	v_exp_f32_e32 v74, v74
	v_exp_f32_e32 v75, v75
	v_pk_mul_f32 v[60:61], v[60:61], v[88:89] op_sel_hi:[1,0]
	v_pk_mul_f32 v[62:63], v[62:63], v[88:89] op_sel_hi:[1,0]
	v_exp_f32_e32 v64, v64
	v_exp_f32_e32 v65, v65
	v_exp_f32_e32 v66, v66
	v_exp_f32_e32 v67, v67
	v_pk_mul_f32 v[56:57], v[56:57], v[88:89] op_sel_hi:[1,0]
	v_pk_mul_f32 v[58:59], v[58:59], v[88:89] op_sel_hi:[1,0]
	v_exp_f32_e32 v100, v100
	v_exp_f32_e32 v101, v101
	v_exp_f32_e32 v102, v102
	v_exp_f32_e32 v103, v103
	v_cvt_pk_bf16_f32 v222, v68, v69
	v_cvt_pk_bf16_f32 v223, v70, v71
	v_cvt_pk_bf16_f32 v224, v64, v65
	v_cvt_pk_bf16_f32 v225, v66, v67
	v_mul_f32_e32 v28, v28, v186
	v_mul_f32_e32 v29, v29, v186
	v_mul_f32_e32 v30, v30, v186
	v_mul_f32_e32 v31, v31, v186
	s_waitcnt lgkmcnt(7)
	v_mfma_f32_16x16x32_bf16 v[60:63], v[104:107], v[222:225], v[60:63]
	v_cvt_pk_bf16_f32 v226, v72, v73
	v_cvt_pk_bf16_f32 v227, v74, v75
	s_waitcnt lgkmcnt(5)
	v_mfma_f32_16x16x32_bf16 v[56:59], v[84:87], v[222:225], v[56:59]
	v_cvt_pk_bf16_f32 v228, v100, v101
	v_cvt_pk_bf16_f32 v229, v102, v103
	v_mul_f32_e32 v24, v24, v186
	v_mul_f32_e32 v25, v25, v186
	v_mul_f32_e32 v26, v26, v186
	v_mul_f32_e32 v27, v27, v186
	s_nop 1
	v_mfma_f32_16x16x32_bf16 v[28:31], v[104:107], v[226:229], v[28:31]
	v_add_f32_e32 v92, v92, v90
	v_add_f32_e32 v93, v93, v90
	v_add_f32_e32 v94, v94, v90
	v_add_f32_e32 v95, v95, v90
	v_mul_f32_e32 v52, v52, v88
	v_mul_f32_e32 v53, v53, v88
	v_mul_f32_e32 v54, v54, v88
	v_mul_f32_e32 v55, v55, v88
	v_mfma_f32_16x16x32_bf16 v[24:27], v[84:87], v[226:229], v[24:27]
	v_add_f32_e32 v96, v96, v90
	v_add_f32_e32 v97, v97, v90
	v_add_f32_e32 v98, v98, v90
	v_add_f32_e32 v99, v99, v90
	v_mul_f32_e32 v48, v48, v88
	v_mul_f32_e32 v49, v49, v88
	v_mul_f32_e32 v50, v50, v88
	v_mul_f32_e32 v51, v51, v88
	s_waitcnt lgkmcnt(3)
	v_mfma_f32_16x16x32_bf16 v[52:55], v[206:209], v[222:225], v[52:55]
	v_exp_f32_e32 v92, v92
	v_exp_f32_e32 v93, v93
	v_exp_f32_e32 v94, v94
	v_exp_f32_e32 v95, v95
	s_waitcnt lgkmcnt(1)
	v_mfma_f32_16x16x32_bf16 v[48:51], v[214:217], v[222:225], v[48:51]
	v_exp_f32_e32 v96, v96
	v_exp_f32_e32 v97, v97
	v_exp_f32_e32 v98, v98
	v_exp_f32_e32 v99, v99
	v_add_f32_e32 v76, v76, v178
	v_add_f32_e32 v77, v77, v178
	v_add_f32_e32 v78, v78, v178
	v_add_f32_e32 v79, v79, v178
	v_add_f32_e32 v80, v80, v178
	v_add_f32_e32 v81, v81, v178
	v_add_f32_e32 v82, v82, v178
	v_add_f32_e32 v83, v83, v178
	v_cvt_pk_bf16_f32 v222, v92, v93
	v_cvt_pk_bf16_f32 v223, v94, v95
	v_cvt_pk_bf16_f32 v224, v96, v97
	v_cvt_pk_bf16_f32 v225, v98, v99
	v_exp_f32_e32 v76, v76
	v_exp_f32_e32 v77, v77
	s_nop 1
	v_mfma_f32_16x16x32_bf16 v[60:63], v[198:201], v[222:225], v[60:63]
	v_exp_f32_e32 v78, v78
	v_exp_f32_e32 v79, v79
	v_mfma_f32_16x16x32_bf16 v[56:59], v[202:205], v[222:225], v[56:59]
	v_exp_f32_e32 v80, v80
	v_exp_f32_e32 v81, v81
	v_mfma_f32_16x16x32_bf16 v[52:55], v[210:213], v[222:225], v[52:55]
	v_exp_f32_e32 v82, v82
	v_exp_f32_e32 v83, v83
	s_waitcnt lgkmcnt(0)
	v_mfma_f32_16x16x32_bf16 v[48:51], v[218:221], v[222:225], v[48:51]
	ds_read_b128 v[234:237], v116 offset:2304
	ds_read_b128 v[238:241], v116
	v_mul_f32_e32 v20, v20, v186
	v_mul_f32_e32 v21, v21, v186
	v_mul_f32_e32 v22, v22, v186
	v_mul_f32_e32 v23, v23, v186
	v_mul_f32_e32 v16, v16, v186
	v_mul_f32_e32 v17, v17, v186
	v_mul_f32_e32 v18, v18, v186
	v_mul_f32_e32 v19, v19, v186
	s_nop 1
	v_mfma_f32_16x16x32_bf16 v[20:23], v[206:209], v[226:229], v[20:23]
	v_add_f32_e32 v90, v68, v70
	v_add_f32_e32 v91, v69, v71
	v_add_f32_e32 v178, v72, v74
	v_add_f32_e32 v179, v73, v75
	v_mfma_f32_16x16x32_bf16 v[16:19], v[214:217], v[226:229], v[16:19]
	v_cvt_pk_bf16_f32 v226, v76, v77
	v_cvt_pk_bf16_f32 v227, v78, v79
	v_cvt_pk_bf16_f32 v228, v80, v81
	v_cvt_pk_bf16_f32 v229, v82, v83
	v_add_f32_e32 v90, v90, v64
	v_add_f32_e32 v91, v91, v65
	v_add_f32_e32 v178, v178, v100
	v_add_f32_e32 v179, v179, v101
	s_nop 1
	v_mfma_f32_16x16x32_bf16 v[28:31], v[198:201], v[226:229], v[28:31]
	v_add_f32_e32 v90, v90, v66
	v_add_f32_e32 v91, v91, v67
	v_add_f32_e32 v178, v178, v102
	v_add_f32_e32 v179, v179, v103
	v_mfma_f32_16x16x32_bf16 v[24:27], v[202:205], v[226:229], v[24:27]
	v_add_f32_e32 v90, v90, v92
	v_add_f32_e32 v91, v91, v93
	v_add_f32_e32 v178, v178, v76
	v_add_f32_e32 v179, v179, v77
	v_mfma_f32_16x16x32_bf16 v[20:23], v[210:213], v[226:229], v[20:23]
	v_add_f32_e32 v90, v90, v94
	v_add_f32_e32 v91, v91, v95
	v_add_f32_e32 v178, v178, v78
	v_add_f32_e32 v179, v179, v79
	v_mfma_f32_16x16x32_bf16 v[16:19], v[218:221], v[226:229], v[16:19]
	v_add_f32_e32 v90, v90, v96
	v_add_f32_e32 v91, v91, v97
	v_add_f32_e32 v178, v178, v80
	v_add_f32_e32 v179, v179, v81
	v_add_f32_e32 v90, v90, v98
	v_add_f32_e32 v91, v91, v99
	v_add_f32_e32 v178, v178, v82
	v_add_f32_e32 v179, v179, v83
	v_add_f32_e32 v64, v90, v91
	v_add_f32_e32 v65, v178, v179
	v_fma_f32 v158, v158, v88, v64
	v_fma_f32 v159, v159, v89, v65
	s_cmpk_lg_i32 s0, 0x80
	s_cbranch_scc1 .Lpast_qskip
	s_cmp_lg_u64 s[22:23], 0
	s_cbranch_scc1 .Lpast_qskip
	v_mov_b32_e32 v233, 0
	s_waitcnt vmcnt(1)
	v_and_b32_e32 v137, 0xfff, v141
	v_lshlrev_b32_e32 v232, 7, v137
	v_lshl_add_u64 v[4:5], v[156:157], 0, v[232:233]
	global_load_dwordx4 v[0:3], v[4:5], off
	s_nop 0
	global_load_dwordx4 v[4:7], v[4:5], off offset:64
	s_waitcnt vmcnt(2)
	v_and_b32_e32 v139, 0xfff, v149
	v_lshlrev_b32_e32 v232, 7, v139
	v_lshl_add_u64 v[12:13], v[156:157], 0, v[232:233]
	global_load_dwordx4 v[8:11], v[12:13], off
	s_nop 0
	global_load_dwordx4 v[12:15], v[12:13], off offset:64
